# attention epilogue de-serialised (8 gate loads hoisted, one wait; permlane row-sum reduce); scans statically on blocks 0..31 whose CU-mates (256..287) sit P4 out
# speedup vs baseline: 1.0218x; 1.0149x over previous
.LBB0_8:
	s_or_b64 exec, exec, s[4:5]
	s_add_u32 s4, s24, 0x4000
	s_addc_u32 s5, s25, 0
	v_writelane_b32 v237, s4, 8
	s_cmp_eq_u32 s2, 0
	v_mov_b32_e32 v2, v178
	v_writelane_b32 v237, s5, 9
	s_cselect_b64 s[4:5], -1, 0
	s_nop 0
	v_cmp_gt_i32_e32 vcc, 64, v2
	s_and_b64 s[6:7], s[4:5], vcc
	s_and_saveexec_b64 s[4:5], s[6:7]
	s_cbranch_execz .LBB0_10
	v_readlane_b32 s6, v237, 8
	v_ashrrev_i32_e32 v3, 31, v2
	v_readlane_b32 s7, v237, 9
	v_mov_b32_e32 v1, 0
	s_cmp_eq_u32 s26, 0x200
	s_cselect_b32 s8, 32, 0
	v_mov_b32_e32 v1, s8
	s_nop 0
	v_lshl_add_u64 v[2:3], v[2:3], 2, s[6:7]
	global_store_dword v[2:3], v1, off

.LBB0_655:
	s_or_b64 exec, exec, s[0:1]
	v_readlane_b32 s0, v234, 30
	v_readlane_b32 s1, v234, 62
	s_or_b32 s34, s1, s0
	s_lshl_b64 s[0:1], s[34:35], 2
	v_readlane_b32 s12, v237, 8
	v_readlane_b32 s13, v237, 9
	s_add_u32 s44, s12, s0
	s_addc_u32 s45, s13, s1
	v_readlane_b32 s0, v234, 31
	v_readlane_b32 s12, v234, 63
	v_readlane_b32 s1, v234, 32
	v_readlane_b32 s13, v233, 0
	s_and_b64 s[0:1], s[0:1], s[12:13]
	s_and_b64 s[0:1], s[0:1], exec
	s_movk_i32 s0, 0x620
	s_cselect_b32 s68, s0, 0x420
	s_mov_b64 s[46:47], 0
	s_mov_b32 s0, 0
	s_cmp_lg_u32 s26, 0x200
	s_cbranch_scc1 .Lp4s_set
	s_and_b32 s1, s89, 0x1e0
	s_cmp_eq_u32 s1, 0x100
	s_cbranch_scc1 .LBB0_945
	s_cmp_lg_u32 s1, 0
	s_cbranch_scc1 .Lp4s_set
	s_add_u32 s0, s89, 1
.Lp4s_set:
	v_writelane_b32 v233, s0, 58
	s_waitcnt lgkmcnt(0)
	s_barrier
	s_branch .LBB0_659

.LBB0_659:
	s_barrier
	s_and_saveexec_b64 s[0:1], s[92:93]
	s_cbranch_execz .LBB0_663
	v_readlane_b32 s12, v233, 58
	s_nop 3
	s_cmp_eq_u32 s12, 0
	s_cbranch_scc1 .Lp4s_fetch
	s_sub_u32 s12, s12, 1
	v_mov_b32_e32 v0, s12
	s_mov_b32 s12, 0
	v_writelane_b32 v233, s12, 58
	s_branch .Lp4s_store
.Lp4s_fetch:
	s_mov_b64 s[40:41], exec
	v_mbcnt_lo_u32_b32 v0, s40, 0
	v_mbcnt_hi_u32_b32 v0, s41, v0
	v_cmp_eq_u32_e32 vcc, 0, v0
	s_and_saveexec_b64 s[12:13], vcc
	s_cbranch_execz .LBB0_662
	s_bcnt1_i32_b64 s34, s[40:41]
	v_mov_b32_e32 v1, s34
	global_atomic_add v1, v3, v1, s[44:45] sc0

.Lp4s_store:
	v_readlane_b32 s12, v235, 57
	v_readlane_b32 s13, v235, 58
	s_nop 1
	v_mov_b32_e32 v181, s13
	flat_store_dword v[180:181], v0 sc0 sc1
	s_waitcnt vmcnt(0)

.LBB0_870:
	s_or_b64 exec, exec, s[54:55]
	v_readlane_b32 s12, v235, 2
	v_readlane_b32 s13, v235, 3
	v_readlane_b32 s0, v236, 44
	v_readlane_b32 s1, v236, 45
	v_lshlrev_b32_e32 v32, 7, v181
	v_lshl_add_u32 v32, v187, 1, v32
	v_mul_lo_u32 v33, v166, s78
	v_lshl_add_u32 v35, v166, 11, v32
	v_add_u32_e32 v33, v33, v32
	v_add_u32_e32 v36, 0x8000, v35
	v_add_u32_e32 v34, 0x1b000, v33
	s_add_u32 s0, s0, 0x1640
	s_addc_u32 s1, s1, 0
	s_nop 1
	global_load_dwordx2 v[100:101], v33, s[0:1]
	global_load_dwordx2 v[102:103], v33, s[0:1] offset:32
	global_load_dwordx2 v[104:105], v33, s[0:1] offset:64
	global_load_dwordx2 v[106:107], v33, s[0:1] offset:96
	global_load_dwordx2 v[108:109], v34, s[0:1]
	global_load_dwordx2 v[110:111], v34, s[0:1] offset:32
	global_load_dwordx2 v[112:113], v34, s[0:1] offset:64
	global_load_dwordx2 v[114:115], v34, s[0:1] offset:96
	v_mov_b32_e32 v38, v165
	s_nop 1
	v_permlane16_swap_b32_e32 v165, v38
	s_nop 1
	v_add_f32_e32 v165, v165, v38
	s_nop 0
	v_mov_b32_e32 v38, v165
	s_nop 1
	v_permlane32_swap_b32_e32 v165, v38
	s_nop 1
	v_add_f32_e32 v165, v165, v38
	v_mov_b32_e32 v40, v164
	s_nop 1
	v_permlane16_swap_b32_e32 v164, v40
	s_nop 1
	v_add_f32_e32 v164, v164, v40
	s_nop 0
	v_mov_b32_e32 v40, v164
	s_nop 1
	v_permlane32_swap_b32_e32 v164, v40
	s_nop 1
	v_add_f32_e32 v164, v164, v40
	s_nop 0
	v_div_scale_f32 v44, s[40:41], v165, v165, 1.0
	v_rcp_f32_e32 v45, v44
	s_nop 0
	v_fma_f32 v46, -v44, v45, 1.0
	v_fmac_f32_e32 v45, v46, v45
	v_div_scale_f32 v46, vcc, 1.0, v165, 1.0
	v_mul_f32_e32 v47, v46, v45
	v_fma_f32 v48, -v44, v47, v46
	v_fmac_f32_e32 v47, v48, v45
	v_fma_f32 v44, -v44, v47, v46
	v_div_fmas_f32 v44, v44, v45, v47
	v_div_fixup_f32 v41, v44, v165, 1.0
	s_nop 0
	v_div_scale_f32 v44, s[40:41], v164, v164, 1.0
	v_rcp_f32_e32 v45, v44
	s_nop 0
	v_fma_f32 v46, -v44, v45, 1.0
	v_fmac_f32_e32 v45, v46, v45
	v_div_scale_f32 v46, vcc, 1.0, v164, 1.0
	v_mul_f32_e32 v47, v46, v45
	v_fma_f32 v48, -v44, v47, v46
	v_fmac_f32_e32 v47, v48, v45
	v_fma_f32 v44, -v44, v47, v46
	v_div_fmas_f32 v44, v44, v45, v47
	v_div_fixup_f32 v42, v44, v164, 1.0
	s_waitcnt vmcnt(0)
	v_lshlrev_b32_e32 v44, 16, v100
	v_and_b32_e32 v45, 0xffff0000, v100
	v_lshlrev_b32_e32 v46, 16, v101
	v_and_b32_e32 v47, 0xffff0000, v101
	v_mul_f32_e32 v48, 0xbfb8aa3b, v44
	v_mul_f32_e32 v49, 0xbfb8aa3b, v45
	v_mul_f32_e32 v50, 0xbfb8aa3b, v46
	v_mul_f32_e32 v51, 0xbfb8aa3b, v47
	v_exp_f32_e32 v48, v48
	v_exp_f32_e32 v49, v49
	v_exp_f32_e32 v50, v50
	v_exp_f32_e32 v51, v51
	v_mul_f32_e32 v52, v96, v41
	v_mul_f32_e32 v53, v97, v41
	v_mul_f32_e32 v54, v98, v41
	v_mul_f32_e32 v55, v99, v41
	v_add_f32_e32 v48, 1.0, v48
	v_add_f32_e32 v49, 1.0, v49
	v_add_f32_e32 v50, 1.0, v50
	v_add_f32_e32 v51, 1.0, v51
	v_rcp_f32_e32 v48, v48
	v_rcp_f32_e32 v49, v49
	v_rcp_f32_e32 v50, v50
	v_rcp_f32_e32 v51, v51
	s_nop 0
	v_mul_f32_e32 v48, v48, v44
	v_mul_f32_e32 v49, v49, v45
	v_mul_f32_e32 v50, v50, v46
	v_mul_f32_e32 v51, v51, v47
	v_mul_f32_e32 v52, v52, v48
	v_mul_f32_e32 v53, v53, v49
	v_mul_f32_e32 v54, v54, v50
	v_mul_f32_e32 v55, v55, v51
	v_cvt_pk_bf16_f32 v56, v52, v53
	v_cvt_pk_bf16_f32 v57, v54, v55
	global_store_dwordx2 v35, v[56:57], s[12:13] offset:1024
	v_lshlrev_b32_e32 v44, 16, v102
	v_and_b32_e32 v45, 0xffff0000, v102
	v_lshlrev_b32_e32 v46, 16, v103
	v_and_b32_e32 v47, 0xffff0000, v103
	v_mul_f32_e32 v48, 0xbfb8aa3b, v44
	v_mul_f32_e32 v49, 0xbfb8aa3b, v45
	v_mul_f32_e32 v50, 0xbfb8aa3b, v46
	v_mul_f32_e32 v51, 0xbfb8aa3b, v47
	v_exp_f32_e32 v48, v48
	v_exp_f32_e32 v49, v49
	v_exp_f32_e32 v50, v50
	v_exp_f32_e32 v51, v51
	v_mul_f32_e32 v52, v28, v41
	v_mul_f32_e32 v53, v29, v41
	v_mul_f32_e32 v54, v30, v41
	v_mul_f32_e32 v55, v31, v41
	v_add_f32_e32 v48, 1.0, v48
	v_add_f32_e32 v49, 1.0, v49
	v_add_f32_e32 v50, 1.0, v50
	v_add_f32_e32 v51, 1.0, v51
	v_rcp_f32_e32 v48, v48
	v_rcp_f32_e32 v49, v49
	v_rcp_f32_e32 v50, v50
	v_rcp_f32_e32 v51, v51
	s_nop 0
	v_mul_f32_e32 v48, v48, v44
	v_mul_f32_e32 v49, v49, v45
	v_mul_f32_e32 v50, v50, v46
	v_mul_f32_e32 v51, v51, v47
	v_mul_f32_e32 v52, v52, v48
	v_mul_f32_e32 v53, v53, v49
	v_mul_f32_e32 v54, v54, v50
	v_mul_f32_e32 v55, v55, v51
	v_cvt_pk_bf16_f32 v56, v52, v53
	v_cvt_pk_bf16_f32 v57, v54, v55
	global_store_dwordx2 v35, v[56:57], s[12:13] offset:1056
	v_lshlrev_b32_e32 v44, 16, v104
	v_and_b32_e32 v45, 0xffff0000, v104
	v_lshlrev_b32_e32 v46, 16, v105
	v_and_b32_e32 v47, 0xffff0000, v105
	v_mul_f32_e32 v48, 0xbfb8aa3b, v44
	v_mul_f32_e32 v49, 0xbfb8aa3b, v45
	v_mul_f32_e32 v50, 0xbfb8aa3b, v46
	v_mul_f32_e32 v51, 0xbfb8aa3b, v47
	v_exp_f32_e32 v48, v48
	v_exp_f32_e32 v49, v49
	v_exp_f32_e32 v50, v50
	v_exp_f32_e32 v51, v51
	v_mul_f32_e32 v52, v24, v41
	v_mul_f32_e32 v53, v25, v41
	v_mul_f32_e32 v54, v26, v41
	v_mul_f32_e32 v55, v27, v41
	v_add_f32_e32 v48, 1.0, v48
	v_add_f32_e32 v49, 1.0, v49
	v_add_f32_e32 v50, 1.0, v50
	v_add_f32_e32 v51, 1.0, v51
	v_rcp_f32_e32 v48, v48
	v_rcp_f32_e32 v49, v49
	v_rcp_f32_e32 v50, v50
	v_rcp_f32_e32 v51, v51
	s_nop 0
	v_mul_f32_e32 v48, v48, v44
	v_mul_f32_e32 v49, v49, v45
	v_mul_f32_e32 v50, v50, v46
	v_mul_f32_e32 v51, v51, v47
	v_mul_f32_e32 v52, v52, v48
	v_mul_f32_e32 v53, v53, v49
	v_mul_f32_e32 v54, v54, v50
	v_mul_f32_e32 v55, v55, v51
	v_cvt_pk_bf16_f32 v56, v52, v53
	v_cvt_pk_bf16_f32 v57, v54, v55
	global_store_dwordx2 v35, v[56:57], s[12:13] offset:1088
	v_lshlrev_b32_e32 v44, 16, v106
	v_and_b32_e32 v45, 0xffff0000, v106
	v_lshlrev_b32_e32 v46, 16, v107
	v_and_b32_e32 v47, 0xffff0000, v107
	v_mul_f32_e32 v48, 0xbfb8aa3b, v44
	v_mul_f32_e32 v49, 0xbfb8aa3b, v45
	v_mul_f32_e32 v50, 0xbfb8aa3b, v46
	v_mul_f32_e32 v51, 0xbfb8aa3b, v47
	v_exp_f32_e32 v48, v48
	v_exp_f32_e32 v49, v49
	v_exp_f32_e32 v50, v50
	v_exp_f32_e32 v51, v51
	v_mul_f32_e32 v52, v20, v41
	v_mul_f32_e32 v53, v21, v41
	v_mul_f32_e32 v54, v22, v41
	v_mul_f32_e32 v55, v23, v41
	v_add_f32_e32 v48, 1.0, v48
	v_add_f32_e32 v49, 1.0, v49
	v_add_f32_e32 v50, 1.0, v50
	v_add_f32_e32 v51, 1.0, v51
	v_rcp_f32_e32 v48, v48
	v_rcp_f32_e32 v49, v49
	v_rcp_f32_e32 v50, v50
	v_rcp_f32_e32 v51, v51
	s_nop 0
	v_mul_f32_e32 v48, v48, v44
	v_mul_f32_e32 v49, v49, v45
	v_mul_f32_e32 v50, v50, v46
	v_mul_f32_e32 v51, v51, v47
	v_mul_f32_e32 v52, v52, v48
	v_mul_f32_e32 v53, v53, v49
	v_mul_f32_e32 v54, v54, v50
	v_mul_f32_e32 v55, v55, v51
	v_cvt_pk_bf16_f32 v56, v52, v53
	v_cvt_pk_bf16_f32 v57, v54, v55
	global_store_dwordx2 v35, v[56:57], s[12:13] offset:1120
	v_lshlrev_b32_e32 v44, 16, v108
	v_and_b32_e32 v45, 0xffff0000, v108
	v_lshlrev_b32_e32 v46, 16, v109
	v_and_b32_e32 v47, 0xffff0000, v109
	v_mul_f32_e32 v48, 0xbfb8aa3b, v44
	v_mul_f32_e32 v49, 0xbfb8aa3b, v45
	v_mul_f32_e32 v50, 0xbfb8aa3b, v46
	v_mul_f32_e32 v51, 0xbfb8aa3b, v47
	v_exp_f32_e32 v48, v48
	v_exp_f32_e32 v49, v49
	v_exp_f32_e32 v50, v50
	v_exp_f32_e32 v51, v51
	v_mul_f32_e32 v52, v16, v42
	v_mul_f32_e32 v53, v17, v42
	v_mul_f32_e32 v54, v18, v42
	v_mul_f32_e32 v55, v19, v42
	v_add_f32_e32 v48, 1.0, v48
	v_add_f32_e32 v49, 1.0, v49
	v_add_f32_e32 v50, 1.0, v50
	v_add_f32_e32 v51, 1.0, v51
	v_rcp_f32_e32 v48, v48
	v_rcp_f32_e32 v49, v49
	v_rcp_f32_e32 v50, v50
	v_rcp_f32_e32 v51, v51
	s_nop 0
	v_mul_f32_e32 v48, v48, v44
	v_mul_f32_e32 v49, v49, v45
	v_mul_f32_e32 v50, v50, v46
	v_mul_f32_e32 v51, v51, v47
	v_mul_f32_e32 v52, v52, v48
	v_mul_f32_e32 v53, v53, v49
	v_mul_f32_e32 v54, v54, v50
	v_mul_f32_e32 v55, v55, v51
	v_cvt_pk_bf16_f32 v56, v52, v53
	v_cvt_pk_bf16_f32 v57, v54, v55
	global_store_dwordx2 v36, v[56:57], s[12:13] offset:1024
	v_lshlrev_b32_e32 v44, 16, v110
	v_and_b32_e32 v45, 0xffff0000, v110
	v_lshlrev_b32_e32 v46, 16, v111
	v_and_b32_e32 v47, 0xffff0000, v111
	v_mul_f32_e32 v48, 0xbfb8aa3b, v44
	v_mul_f32_e32 v49, 0xbfb8aa3b, v45
	v_mul_f32_e32 v50, 0xbfb8aa3b, v46
	v_mul_f32_e32 v51, 0xbfb8aa3b, v47
	v_exp_f32_e32 v48, v48
	v_exp_f32_e32 v49, v49
	v_exp_f32_e32 v50, v50
	v_exp_f32_e32 v51, v51
	v_mul_f32_e32 v52, v12, v42
	v_mul_f32_e32 v53, v13, v42
	v_mul_f32_e32 v54, v14, v42
	v_mul_f32_e32 v55, v15, v42
	v_add_f32_e32 v48, 1.0, v48
	v_add_f32_e32 v49, 1.0, v49
	v_add_f32_e32 v50, 1.0, v50
	v_add_f32_e32 v51, 1.0, v51
	v_rcp_f32_e32 v48, v48
	v_rcp_f32_e32 v49, v49
	v_rcp_f32_e32 v50, v50
	v_rcp_f32_e32 v51, v51
	s_nop 0
	v_mul_f32_e32 v48, v48, v44
	v_mul_f32_e32 v49, v49, v45
	v_mul_f32_e32 v50, v50, v46
	v_mul_f32_e32 v51, v51, v47
	v_mul_f32_e32 v52, v52, v48
	v_mul_f32_e32 v53, v53, v49
	v_mul_f32_e32 v54, v54, v50
	v_mul_f32_e32 v55, v55, v51
	v_cvt_pk_bf16_f32 v56, v52, v53
	v_cvt_pk_bf16_f32 v57, v54, v55
	global_store_dwordx2 v36, v[56:57], s[12:13] offset:1056
	v_lshlrev_b32_e32 v44, 16, v112
	v_and_b32_e32 v45, 0xffff0000, v112
	v_lshlrev_b32_e32 v46, 16, v113
	v_and_b32_e32 v47, 0xffff0000, v113
	v_mul_f32_e32 v48, 0xbfb8aa3b, v44
	v_mul_f32_e32 v49, 0xbfb8aa3b, v45
	v_mul_f32_e32 v50, 0xbfb8aa3b, v46
	v_mul_f32_e32 v51, 0xbfb8aa3b, v47
	v_exp_f32_e32 v48, v48
	v_exp_f32_e32 v49, v49
	v_exp_f32_e32 v50, v50
	v_exp_f32_e32 v51, v51
	v_mul_f32_e32 v52, v8, v42
	v_mul_f32_e32 v53, v9, v42
	v_mul_f32_e32 v54, v10, v42
	v_mul_f32_e32 v55, v11, v42
	v_add_f32_e32 v48, 1.0, v48
	v_add_f32_e32 v49, 1.0, v49
	v_add_f32_e32 v50, 1.0, v50
	v_add_f32_e32 v51, 1.0, v51
	v_rcp_f32_e32 v48, v48
	v_rcp_f32_e32 v49, v49
	v_rcp_f32_e32 v50, v50
	v_rcp_f32_e32 v51, v51
	s_nop 0
	v_mul_f32_e32 v48, v48, v44
	v_mul_f32_e32 v49, v49, v45
	v_mul_f32_e32 v50, v50, v46
	v_mul_f32_e32 v51, v51, v47
	v_mul_f32_e32 v52, v52, v48
	v_mul_f32_e32 v53, v53, v49
	v_mul_f32_e32 v54, v54, v50
	v_mul_f32_e32 v55, v55, v51
	v_cvt_pk_bf16_f32 v56, v52, v53
	v_cvt_pk_bf16_f32 v57, v54, v55
	global_store_dwordx2 v36, v[56:57], s[12:13] offset:1088
	v_lshlrev_b32_e32 v44, 16, v114
	v_and_b32_e32 v45, 0xffff0000, v114
	v_lshlrev_b32_e32 v46, 16, v115
	v_and_b32_e32 v47, 0xffff0000, v115
	v_mul_f32_e32 v48, 0xbfb8aa3b, v44
	v_mul_f32_e32 v49, 0xbfb8aa3b, v45
	v_mul_f32_e32 v50, 0xbfb8aa3b, v46
	v_mul_f32_e32 v51, 0xbfb8aa3b, v47
	v_exp_f32_e32 v48, v48
	v_exp_f32_e32 v49, v49
	v_exp_f32_e32 v50, v50
	v_exp_f32_e32 v51, v51
	v_mul_f32_e32 v52, v4, v42
	v_mul_f32_e32 v53, v5, v42
	v_mul_f32_e32 v54, v6, v42
	v_mul_f32_e32 v55, v7, v42
	v_add_f32_e32 v48, 1.0, v48
	v_add_f32_e32 v49, 1.0, v49
	v_add_f32_e32 v50, 1.0, v50
	v_add_f32_e32 v51, 1.0, v51
	v_rcp_f32_e32 v48, v48
	v_rcp_f32_e32 v49, v49
	v_rcp_f32_e32 v50, v50
	v_rcp_f32_e32 v51, v51
	s_nop 0
	v_mul_f32_e32 v48, v48, v44
	v_mul_f32_e32 v49, v49, v45
	v_mul_f32_e32 v50, v50, v46
	v_mul_f32_e32 v51, v51, v47
	v_mul_f32_e32 v52, v52, v48
	v_mul_f32_e32 v53, v53, v49
	v_mul_f32_e32 v54, v54, v50
	v_mul_f32_e32 v55, v55, v51
	v_cvt_pk_bf16_f32 v56, v52, v53
	v_cvt_pk_bf16_f32 v57, v54, v55
	global_store_dwordx2 v36, v[56:57], s[12:13] offset:1120
